# final RMSNorm rewritten: two rows in flight, counted waits that do not drain the stores
# speedup vs baseline: 1.0056x; 1.0022x over previous
; __global__ void __launch_bounds__(NWAVES * 64, 2) mega_fwd(Args args) {
;     ...
;         for (int m = gw; m < MT; m += NGW) {
;             const float rstd = __builtin_amdgcn_rsqf(ssq[m] * (1.0f / DM) + EPS);
;             float* yr = H + (size_t)m * DM;
; #pragma unroll
;             for (int j = 0; j < 2; ++j) {
;                 const v4u w = *(const v4u*)(XB + (size_t)m * DM + j * 512 + lane * 8);
;                 const f32x4 a = (f32x4){bf_lo(w.x), bf_hi(w.x), bf_lo(w.y), bf_hi(w.y)}, b2 = (f32x4){bf_lo(w.z), bf_hi(w.z), bf_lo(w.w), bf_hi(w.w)};
;                 *(f32x4*)(yr + j * 512 + lane * 8) = a * rstd * gf[j][0]; *(f32x4*)(yr + j * 512 + lane * 8 + 4) = b2 * rstd * gf[j][1];
;             }
.LBB0_1411:
	global_load_dword v34, v20, s[0:1]
	global_load_dwordx4 v[36:39], v[16:17], off
	global_load_dwordx4 v[40:43], v[16:17], off offset:1024
	s_add_i32 s34, s34, s12
	s_add_u32 s0, s0, s2
	s_addc_u32 s1, s1, s3
	v_lshl_add_u64 v[16:17], v[16:17], 0, s[4:5]
	s_cmp_gt_i32 s34, 0x83ff
	s_cbranch_scc1 .Lfin_tailA
	global_load_dword v35, v20, s[0:1]
	global_load_dwordx4 v[44:47], v[16:17], off
	global_load_dwordx4 v[48:51], v[16:17], off offset:1024
	s_waitcnt vmcnt(3)
	v_fmamk_f32 v30, v34, 0x3a800000, v21
	v_rsq_f32_e32 v30, v30
	v_lshlrev_b32_e32 v26, 16, v36
	v_and_b32_e32 v27, 0xffff0000, v36
	v_lshlrev_b32_e32 v22, 16, v37
	v_and_b32_e32 v23, 0xffff0000, v37
	v_lshlrev_b32_e32 v28, 16, v38
	v_and_b32_e32 v29, 0xffff0000, v38
	v_lshlrev_b32_e32 v24, 16, v39
	v_and_b32_e32 v25, 0xffff0000, v39
	v_pk_mul_f32 v[26:27], v[30:31], v[26:27] op_sel_hi:[0,1]
	v_pk_mul_f32 v[22:23], v[30:31], v[22:23] op_sel_hi:[0,1]
	v_pk_mul_f32 v[32:33], v[30:31], v[28:29] op_sel_hi:[0,1]
	v_pk_mul_f32 v[28:29], v[30:31], v[24:25] op_sel_hi:[0,1]
	v_pk_mul_f32 v[24:25], v[2:3], v[22:23]
	v_pk_mul_f32 v[22:23], v[0:1], v[26:27]
	v_pk_mul_f32 v[28:29], v[10:11], v[28:29]
	v_pk_mul_f32 v[26:27], v[8:9], v[32:33]
	global_store_dwordx4 v[18:19], v[22:25], off offset:-2048
	global_store_dwordx4 v[18:19], v[26:29], off offset:-2032
	v_lshlrev_b32_e32 v56, 16, v40
	v_and_b32_e32 v57, 0xffff0000, v40
	v_lshlrev_b32_e32 v52, 16, v41
	v_and_b32_e32 v53, 0xffff0000, v41
	v_lshlrev_b32_e32 v58, 16, v42
	v_and_b32_e32 v59, 0xffff0000, v42
	v_lshlrev_b32_e32 v54, 16, v43
	v_and_b32_e32 v55, 0xffff0000, v43
	v_pk_mul_f32 v[56:57], v[30:31], v[56:57] op_sel_hi:[0,1]
	v_pk_mul_f32 v[52:53], v[30:31], v[52:53] op_sel_hi:[0,1]
	v_pk_mul_f32 v[62:63], v[30:31], v[58:59] op_sel_hi:[0,1]
	v_pk_mul_f32 v[58:59], v[30:31], v[54:55] op_sel_hi:[0,1]
	v_pk_mul_f32 v[54:55], v[14:15], v[52:53]
	v_pk_mul_f32 v[52:53], v[12:13], v[56:57]
	v_pk_mul_f32 v[58:59], v[6:7], v[58:59]
	v_pk_mul_f32 v[56:57], v[4:5], v[62:63]
	global_store_dwordx4 v[18:19], v[52:55], off
	global_store_dwordx4 v[18:19], v[56:59], off offset:16
	v_lshl_add_u64 v[18:19], v[18:19], 0, s[6:7]
.Lfin_loop:
	s_add_i32 s34, s34, s12
	s_add_u32 s0, s0, s2
	s_addc_u32 s1, s1, s3
	v_lshl_add_u64 v[16:17], v[16:17], 0, s[4:5]
	s_cmp_gt_i32 s34, 0x83ff
	s_cbranch_scc1 .Lfin_tailB
	global_load_dword v34, v20, s[0:1]
	global_load_dwordx4 v[36:39], v[16:17], off
	global_load_dwordx4 v[40:43], v[16:17], off offset:1024
	s_waitcnt vmcnt(7)
	v_fmamk_f32 v30, v35, 0x3a800000, v21
	v_rsq_f32_e32 v30, v30
	v_lshlrev_b32_e32 v26, 16, v44
	v_and_b32_e32 v27, 0xffff0000, v44
	v_lshlrev_b32_e32 v22, 16, v45
	v_and_b32_e32 v23, 0xffff0000, v45
	v_lshlrev_b32_e32 v28, 16, v46
	v_and_b32_e32 v29, 0xffff0000, v46
	v_lshlrev_b32_e32 v24, 16, v47
	v_and_b32_e32 v25, 0xffff0000, v47
	v_pk_mul_f32 v[26:27], v[30:31], v[26:27] op_sel_hi:[0,1]
	v_pk_mul_f32 v[22:23], v[30:31], v[22:23] op_sel_hi:[0,1]
	v_pk_mul_f32 v[32:33], v[30:31], v[28:29] op_sel_hi:[0,1]
	v_pk_mul_f32 v[28:29], v[30:31], v[24:25] op_sel_hi:[0,1]
	v_pk_mul_f32 v[24:25], v[2:3], v[22:23]
	v_pk_mul_f32 v[22:23], v[0:1], v[26:27]
	v_pk_mul_f32 v[28:29], v[10:11], v[28:29]
	v_pk_mul_f32 v[26:27], v[8:9], v[32:33]
	global_store_dwordx4 v[18:19], v[22:25], off offset:-2048
	global_store_dwordx4 v[18:19], v[26:29], off offset:-2032
	v_lshlrev_b32_e32 v56, 16, v48
	v_and_b32_e32 v57, 0xffff0000, v48
	v_lshlrev_b32_e32 v52, 16, v49
	v_and_b32_e32 v53, 0xffff0000, v49
	v_lshlrev_b32_e32 v58, 16, v50
	v_and_b32_e32 v59, 0xffff0000, v50
	v_lshlrev_b32_e32 v54, 16, v51
	v_and_b32_e32 v55, 0xffff0000, v51
	v_pk_mul_f32 v[56:57], v[30:31], v[56:57] op_sel_hi:[0,1]
	v_pk_mul_f32 v[52:53], v[30:31], v[52:53] op_sel_hi:[0,1]
	v_pk_mul_f32 v[62:63], v[30:31], v[58:59] op_sel_hi:[0,1]
	v_pk_mul_f32 v[58:59], v[30:31], v[54:55] op_sel_hi:[0,1]
	v_pk_mul_f32 v[54:55], v[14:15], v[52:53]
	v_pk_mul_f32 v[52:53], v[12:13], v[56:57]
	v_pk_mul_f32 v[58:59], v[6:7], v[58:59]
	v_pk_mul_f32 v[56:57], v[4:5], v[62:63]
	global_store_dwordx4 v[18:19], v[52:55], off
	global_store_dwordx4 v[18:19], v[56:59], off offset:16
	v_lshl_add_u64 v[18:19], v[18:19], 0, s[6:7]
	s_add_i32 s34, s34, s12
	s_add_u32 s0, s0, s2
	s_addc_u32 s1, s1, s3
	v_lshl_add_u64 v[16:17], v[16:17], 0, s[4:5]
	s_cmp_gt_i32 s34, 0x83ff
	s_cbranch_scc1 .Lfin_tailA
	global_load_dword v35, v20, s[0:1]
	global_load_dwordx4 v[44:47], v[16:17], off
	global_load_dwordx4 v[48:51], v[16:17], off offset:1024
	s_waitcnt vmcnt(7)
	v_fmamk_f32 v30, v34, 0x3a800000, v21
	v_rsq_f32_e32 v30, v30
	v_lshlrev_b32_e32 v26, 16, v36
	v_and_b32_e32 v27, 0xffff0000, v36
	v_lshlrev_b32_e32 v22, 16, v37
	v_and_b32_e32 v23, 0xffff0000, v37
	v_lshlrev_b32_e32 v28, 16, v38
	v_and_b32_e32 v29, 0xffff0000, v38
	v_lshlrev_b32_e32 v24, 16, v39
	v_and_b32_e32 v25, 0xffff0000, v39
	v_pk_mul_f32 v[26:27], v[30:31], v[26:27] op_sel_hi:[0,1]
	v_pk_mul_f32 v[22:23], v[30:31], v[22:23] op_sel_hi:[0,1]
	v_pk_mul_f32 v[32:33], v[30:31], v[28:29] op_sel_hi:[0,1]
	v_pk_mul_f32 v[28:29], v[30:31], v[24:25] op_sel_hi:[0,1]
	v_pk_mul_f32 v[24:25], v[2:3], v[22:23]
	v_pk_mul_f32 v[22:23], v[0:1], v[26:27]
	v_pk_mul_f32 v[28:29], v[10:11], v[28:29]
	v_pk_mul_f32 v[26:27], v[8:9], v[32:33]
	global_store_dwordx4 v[18:19], v[22:25], off offset:-2048
	global_store_dwordx4 v[18:19], v[26:29], off offset:-2032
	v_lshlrev_b32_e32 v56, 16, v40
	v_and_b32_e32 v57, 0xffff0000, v40
	v_lshlrev_b32_e32 v52, 16, v41
	v_and_b32_e32 v53, 0xffff0000, v41
	v_lshlrev_b32_e32 v58, 16, v42
	v_and_b32_e32 v59, 0xffff0000, v42
	v_lshlrev_b32_e32 v54, 16, v43
	v_and_b32_e32 v55, 0xffff0000, v43
	v_pk_mul_f32 v[56:57], v[30:31], v[56:57] op_sel_hi:[0,1]
	v_pk_mul_f32 v[52:53], v[30:31], v[52:53] op_sel_hi:[0,1]
	v_pk_mul_f32 v[62:63], v[30:31], v[58:59] op_sel_hi:[0,1]
	v_pk_mul_f32 v[58:59], v[30:31], v[54:55] op_sel_hi:[0,1]
	v_pk_mul_f32 v[54:55], v[14:15], v[52:53]
	v_pk_mul_f32 v[52:53], v[12:13], v[56:57]
	v_pk_mul_f32 v[58:59], v[6:7], v[58:59]
	v_pk_mul_f32 v[56:57], v[4:5], v[62:63]
	global_store_dwordx4 v[18:19], v[52:55], off
	global_store_dwordx4 v[18:19], v[56:59], off offset:16
	v_lshl_add_u64 v[18:19], v[18:19], 0, s[6:7]
	s_branch .Lfin_loop
; __global__ void __launch_bounds__(NWAVES * 64, 2) mega_fwd(Args args) {
;     ...
;         for (int m = gw; m < MT; m += NGW) {
;             const float rstd = __builtin_amdgcn_rsqf(ssq[m] * (1.0f / DM) + EPS);
;             float* yr = H + (size_t)m * DM;
; #pragma unroll
;             for (int j = 0; j < 2; ++j) {
;                 const v4u w = *(const v4u*)(XB + (size_t)m * DM + j * 512 + lane * 8);
;                 const f32x4 a = (f32x4){bf_lo(w.x), bf_hi(w.x), bf_lo(w.y), bf_hi(w.y)}, b2 = (f32x4){bf_lo(w.z), bf_hi(w.z), bf_lo(w.w), bf_hi(w.w)};
;                 *(f32x4*)(yr + j * 512 + lane * 8) = a * rstd * gf[j][0]; *(f32x4*)(yr + j * 512 + lane * 8 + 4) = b2 * rstd * gf[j][1];
;             }
.Lfin_tailA:
	s_waitcnt vmcnt(0)
	v_fmamk_f32 v30, v34, 0x3a800000, v21
	v_rsq_f32_e32 v30, v30
	v_lshlrev_b32_e32 v26, 16, v36
	v_and_b32_e32 v27, 0xffff0000, v36
	v_lshlrev_b32_e32 v22, 16, v37
	v_and_b32_e32 v23, 0xffff0000, v37
	v_lshlrev_b32_e32 v28, 16, v38
	v_and_b32_e32 v29, 0xffff0000, v38
	v_lshlrev_b32_e32 v24, 16, v39
	v_and_b32_e32 v25, 0xffff0000, v39
	v_pk_mul_f32 v[26:27], v[30:31], v[26:27] op_sel_hi:[0,1]
	v_pk_mul_f32 v[22:23], v[30:31], v[22:23] op_sel_hi:[0,1]
	v_pk_mul_f32 v[32:33], v[30:31], v[28:29] op_sel_hi:[0,1]
	v_pk_mul_f32 v[28:29], v[30:31], v[24:25] op_sel_hi:[0,1]
	v_pk_mul_f32 v[24:25], v[2:3], v[22:23]
	v_pk_mul_f32 v[22:23], v[0:1], v[26:27]
	v_pk_mul_f32 v[28:29], v[10:11], v[28:29]
	v_pk_mul_f32 v[26:27], v[8:9], v[32:33]
	global_store_dwordx4 v[18:19], v[22:25], off offset:-2048
	global_store_dwordx4 v[18:19], v[26:29], off offset:-2032
	v_lshlrev_b32_e32 v56, 16, v40
	v_and_b32_e32 v57, 0xffff0000, v40
	v_lshlrev_b32_e32 v52, 16, v41
	v_and_b32_e32 v53, 0xffff0000, v41
	v_lshlrev_b32_e32 v58, 16, v42
	v_and_b32_e32 v59, 0xffff0000, v42
	v_lshlrev_b32_e32 v54, 16, v43
	v_and_b32_e32 v55, 0xffff0000, v43
	v_pk_mul_f32 v[56:57], v[30:31], v[56:57] op_sel_hi:[0,1]
	v_pk_mul_f32 v[52:53], v[30:31], v[52:53] op_sel_hi:[0,1]
	v_pk_mul_f32 v[62:63], v[30:31], v[58:59] op_sel_hi:[0,1]
	v_pk_mul_f32 v[58:59], v[30:31], v[54:55] op_sel_hi:[0,1]
	v_pk_mul_f32 v[54:55], v[14:15], v[52:53]
	v_pk_mul_f32 v[52:53], v[12:13], v[56:57]
	v_pk_mul_f32 v[58:59], v[6:7], v[58:59]
	v_pk_mul_f32 v[56:57], v[4:5], v[62:63]
	global_store_dwordx4 v[18:19], v[52:55], off
	global_store_dwordx4 v[18:19], v[56:59], off offset:16
	v_lshl_add_u64 v[18:19], v[18:19], 0, s[6:7]
	s_branch .LBB0_1412
.Lfin_tailB:
	s_waitcnt vmcnt(0)
	v_fmamk_f32 v30, v35, 0x3a800000, v21
	v_rsq_f32_e32 v30, v30
	v_lshlrev_b32_e32 v26, 16, v44
	v_and_b32_e32 v27, 0xffff0000, v44
	v_lshlrev_b32_e32 v22, 16, v45
	v_and_b32_e32 v23, 0xffff0000, v45
	v_lshlrev_b32_e32 v28, 16, v46
	v_and_b32_e32 v29, 0xffff0000, v46
	v_lshlrev_b32_e32 v24, 16, v47
	v_and_b32_e32 v25, 0xffff0000, v47
	v_pk_mul_f32 v[26:27], v[30:31], v[26:27] op_sel_hi:[0,1]
	v_pk_mul_f32 v[22:23], v[30:31], v[22:23] op_sel_hi:[0,1]
	v_pk_mul_f32 v[32:33], v[30:31], v[28:29] op_sel_hi:[0,1]
	v_pk_mul_f32 v[28:29], v[30:31], v[24:25] op_sel_hi:[0,1]
	v_pk_mul_f32 v[24:25], v[2:3], v[22:23]
	v_pk_mul_f32 v[22:23], v[0:1], v[26:27]
	v_pk_mul_f32 v[28:29], v[10:11], v[28:29]
	v_pk_mul_f32 v[26:27], v[8:9], v[32:33]
	global_store_dwordx4 v[18:19], v[22:25], off offset:-2048
	global_store_dwordx4 v[18:19], v[26:29], off offset:-2032
	v_lshlrev_b32_e32 v56, 16, v48
	v_and_b32_e32 v57, 0xffff0000, v48
	v_lshlrev_b32_e32 v52, 16, v49
	v_and_b32_e32 v53, 0xffff0000, v49
	v_lshlrev_b32_e32 v58, 16, v50
	v_and_b32_e32 v59, 0xffff0000, v50
	v_lshlrev_b32_e32 v54, 16, v51
	v_and_b32_e32 v55, 0xffff0000, v51
	v_pk_mul_f32 v[56:57], v[30:31], v[56:57] op_sel_hi:[0,1]
	v_pk_mul_f32 v[52:53], v[30:31], v[52:53] op_sel_hi:[0,1]
	v_pk_mul_f32 v[62:63], v[30:31], v[58:59] op_sel_hi:[0,1]
	v_pk_mul_f32 v[58:59], v[30:31], v[54:55] op_sel_hi:[0,1]
	v_pk_mul_f32 v[54:55], v[14:15], v[52:53]
	v_pk_mul_f32 v[52:53], v[12:13], v[56:57]
	v_pk_mul_f32 v[58:59], v[6:7], v[58:59]
	v_pk_mul_f32 v[56:57], v[4:5], v[62:63]
	global_store_dwordx4 v[18:19], v[52:55], off
	global_store_dwordx4 v[18:19], v[56:59], off offset:16
	v_lshl_add_u64 v[18:19], v[18:19], 0, s[6:7]
